# mix_a hgrn_local chunk loop latch waits only for the prefetch loads (vmcnt(4)) instead of draining the 4 tile stores
# speedup vs baseline: 1.0195x; 1.0023x over previous
.LBB0_643:
	s_add_i32 s15, s15, 1
	s_add_i32 s17, s17, 16
	s_add_i32 s16, s16, 64
	s_waitcnt vmcnt(4)
	v_mov_b64_e32 v[36:37], v[4:5]
	v_mov_b64_e32 v[44:45], v[16:17]
	v_mov_b64_e32 v[52:53], v[24:25]
	s_waitcnt vmcnt(4)
	v_mov_b64_e32 v[40:41], v[8:9]
	v_mov_b64_e32 v[48:49], v[20:21]
	v_mov_b64_e32 v[56:57], v[12:13]
	s_cmp_lg_u32 s15, 4
	v_mov_b64_e32 v[34:35], v[2:3]
	v_mov_b64_e32 v[42:43], v[14:15]
	v_mov_b64_e32 v[50:51], v[22:23]
	v_mov_b64_e32 v[38:39], v[6:7]
	v_mov_b64_e32 v[46:47], v[18:19]
	v_mov_b64_e32 v[54:55], v[10:11]
	v_mov_b32_e32 v58, v26
	v_mov_b32_e32 v59, v27
	v_mov_b32_e32 v60, v28
	v_mov_b32_e32 v61, v29
	v_mov_b32_e32 v62, v30
	v_mov_b32_e32 v63, v31
	v_mov_b32_e32 v64, v32
	v_mov_b32_e32 v65, v33
	s_barrier
	s_cbranch_scc0 .LBB0_635
